# attention epilogue: 4 diff_lambda loads hoisted to top of the unit epilogue (were two serialized round trips); on pd1
# speedup vs baseline: 1.0020x; 1.0020x over previous
.LBB0_1107:
	s_add_u32 s40, s22, s8
	s_addc_u32 s41, s23, s9
	v_lshlrev_b32_e32 v164, 2, v150
	global_load_dword v160, v164, s[40:41]
	global_load_dword v161, v164, s[40:41] offset:256
	global_load_dword v162, v164, s[40:41] offset:512
	global_load_dword v163, v164, s[40:41] offset:768
	v_sub_f32_e32 v66, v103, v137
	v_sub_f32_e32 v1, v102, v137
	v_exp_f32_e32 v102, v66
	v_sub_f32_e32 v66, v104, v137
	v_sub_f32_e32 v68, v68, v137
	v_exp_f32_e32 v103, v66
	v_sub_f32_e32 v66, v105, v137
	v_exp_f32_e32 v105, v68
	v_sub_f32_e32 v68, v69, v137
	v_exp_f32_e32 v106, v68
	v_sub_f32_e32 v68, v70, v137
	v_sub_f32_e32 v70, v82, v136
	v_exp_f32_e32 v109, v70
	v_sub_f32_e32 v70, v83, v136
	v_exp_f32_e32 v110, v70
	v_sub_f32_e32 v70, v84, v136
	v_exp_f32_e32 v111, v70
	v_sub_f32_e32 v70, v85, v136
	v_exp_f32_e32 v104, v66
	v_sub_f32_e32 v66, v98, v137
	v_exp_f32_e32 v112, v70
	v_sub_f32_e32 v70, v86, v136
	ds_read_b128 v[80:83], v131 offset:17408
	v_exp_f32_e32 v98, v66
	v_sub_f32_e32 v66, v99, v137
	v_exp_f32_e32 v113, v70
	v_sub_f32_e32 v70, v87, v136
	v_exp_f32_e32 v99, v66
	v_sub_f32_e32 v66, v100, v137
	v_exp_f32_e32 v114, v70
	v_sub_f32_e32 v70, v88, v136
	v_exp_f32_e32 v100, v66
	v_sub_f32_e32 v66, v101, v137
	v_exp_f32_e32 v88, v70
	v_sub_f32_e32 v70, v89, v136
	v_exp_f32_e32 v1, v1
	v_exp_f32_e32 v101, v66
	v_exp_f32_e32 v89, v70
	v_cvt_pk_bf16_f32 v77, v103, v104
	v_cvt_pk_bf16_f32 v76, v1, v102
	v_cvt_pk_bf16_f32 v78, v98, v99
	v_cvt_pk_bf16_f32 v79, v100, v101
	v_cvt_pk_bf16_f32 v120, v109, v110
	v_cvt_pk_bf16_f32 v121, v111, v112
	v_cvt_pk_bf16_f32 v122, v113, v114
	v_cvt_pk_bf16_f32 v123, v88, v89
	s_waitcnt lgkmcnt(0)
	v_mfma_f32_16x16x32_bf16 v[26:29], v[80:83], v[76:79], v[26:29]
	v_sub_f32_e32 v66, v94, v137
	v_sub_f32_e32 v70, v90, v136
	v_sub_f32_e32 v72, v72, v136
	v_mfma_f32_16x16x32_bf16 v[18:21], v[80:83], v[120:123], v[18:21]
	ds_read_b128 v[80:83], v131 offset:19712
	v_exp_f32_e32 v94, v66
	v_sub_f32_e32 v66, v95, v137
	v_exp_f32_e32 v90, v70
	v_sub_f32_e32 v70, v91, v136
	v_exp_f32_e32 v115, v72
	v_sub_f32_e32 v72, v73, v136
	v_exp_f32_e32 v95, v66
	v_sub_f32_e32 v66, v96, v137
	v_exp_f32_e32 v91, v70
	v_sub_f32_e32 v70, v92, v136
	v_exp_f32_e32 v116, v72
	v_sub_f32_e32 v72, v74, v136
	v_exp_f32_e32 v96, v66
	v_sub_f32_e32 v66, v97, v137
	v_exp_f32_e32 v107, v68
	v_sub_f32_e32 v68, v71, v137
	v_exp_f32_e32 v92, v70
	v_sub_f32_e32 v70, v93, v136
	v_exp_f32_e32 v117, v72
	v_sub_f32_e32 v72, v75, v136
	s_waitcnt lgkmcnt(0)
	v_mfma_f32_16x16x32_bf16 v[134:137], v[80:83], v[120:123], v[2:5]
	v_exp_f32_e32 v97, v66
	v_exp_f32_e32 v108, v68
	v_exp_f32_e32 v93, v70
	ds_read_b128 v[2:5], v131 offset:22016
	s_waitcnt lgkmcnt(0)
	v_mfma_f32_16x16x32_bf16 v[138:141], v[2:5], v[76:79], v[14:17]
	v_exp_f32_e32 v118, v72
	v_cvt_pk_bf16_f32 v66, v94, v95
	v_cvt_pk_bf16_f32 v67, v96, v97
	v_mfma_f32_16x16x32_bf16 v[142:145], v[2:5], v[120:123], v[10:13]
	ds_read_b128 v[2:5], v131 offset:24320
	v_cvt_pk_bf16_f32 v68, v105, v106
	v_cvt_pk_bf16_f32 v69, v107, v108
	s_waitcnt lgkmcnt(0)
	v_mfma_f32_16x16x32_bf16 v[152:155], v[2:5], v[76:79], v[30:33]
	ds_read_b128 v[10:13], v131 offset:17472
	v_cvt_pk_bf16_f32 v70, v90, v91
	v_cvt_pk_bf16_f32 v71, v92, v93
	v_mfma_f32_16x16x32_bf16 v[156:159], v[2:5], v[120:123], v[22:25]
	ds_read_b128 v[2:5], v131 offset:26624
	v_cvt_pk_bf16_f32 v72, v115, v116
	v_cvt_pk_bf16_f32 v73, v117, v118
	v_mfma_f32_16x16x32_bf16 v[124:127], v[80:83], v[76:79], v[6:9]
	ds_read_b128 v[22:25], v131 offset:22080
	v_add_f32_e32 v1, 0, v1
	v_add_f32_e32 v1, v102, v1
	s_waitcnt lgkmcnt(1)
	v_mfma_f32_16x16x32_bf16 v[80:83], v[2:5], v[76:79], v[38:41]
	v_add_f32_e32 v1, v103, v1
	v_add_f32_e32 v1, v104, v1
	v_add_f32_e32 v1, v98, v1
	v_mfma_f32_16x16x32_bf16 v[84:87], v[2:5], v[120:123], v[34:37]
	ds_read_b128 v[2:5], v131 offset:28928
	v_add_f32_e32 v1, v99, v1
	v_add_f32_e32 v1, v100, v1
	s_waitcnt lgkmcnt(0)
	v_mfma_f32_16x16x32_bf16 v[46:49], v[2:5], v[76:79], v[46:49]
	v_add_f32_e32 v1, v101, v1
	v_add_f32_e32 v1, v94, v1
	v_add_f32_e32 v1, v95, v1
	v_mfma_f32_16x16x32_bf16 v[42:45], v[2:5], v[120:123], v[42:45]
	ds_read_b128 v[2:5], v131 offset:31232
	v_add_f32_e32 v1, v96, v1
	v_add_f32_e32 v1, v97, v1
	s_waitcnt lgkmcnt(0)
	v_mfma_f32_16x16x32_bf16 v[30:33], v[2:5], v[76:79], v[54:57]
	s_nop 2
	ds_read_b128 v[54:57], v131 offset:24384
	v_add_f32_e32 v1, v105, v1
	v_add_f32_e32 v1, v106, v1
	v_mfma_f32_16x16x32_bf16 v[34:37], v[2:5], v[120:123], v[50:53]
	ds_read_b128 v[2:5], v131 offset:33536
	v_add_f32_e32 v1, v107, v1
	v_add_f32_e32 v1, v108, v1
	v_mfma_f32_16x16x32_bf16 v[14:17], v[10:13], v[66:69], v[26:29]
	v_add_f32_e32 v1, v133, v1
	s_add_u32 s4, s22, s8
	s_addc_u32 s5, s23, s9
	v_mfma_f32_16x16x32_bf16 v[10:13], v[10:13], v[70:73], v[18:21]
	s_cmp_eq_u32 s59, 1
	s_nop 1
	ds_read_b128 v[18:21], v131 offset:19776
	s_waitcnt lgkmcnt(1)
	v_mfma_f32_16x16x32_bf16 v[6:9], v[2:5], v[76:79], v[62:65]
	v_mfma_f32_16x16x32_bf16 v[50:53], v[54:57], v[66:69], v[152:155]
	v_mfma_f32_16x16x32_bf16 v[74:77], v[54:57], v[70:73], v[156:159]
	ds_read_b128 v[54:57], v131 offset:26688
	v_mfma_f32_16x16x32_bf16 v[2:5], v[2:5], v[120:123], v[58:61]
	s_waitcnt lgkmcnt(0)
	v_mfma_f32_16x16x32_bf16 v[120:123], v[54:57], v[66:69], v[80:83]
	v_mfma_f32_16x16x32_bf16 v[78:81], v[54:57], v[70:73], v[84:87]
	ds_read_b128 v[54:57], v131 offset:28992
	v_mfma_f32_16x16x32_bf16 v[26:29], v[18:21], v[66:69], v[124:127]
	s_waitcnt lgkmcnt(0)
	v_mfma_f32_16x16x32_bf16 v[124:127], v[54:57], v[70:73], v[42:45]
	s_nop 2
	ds_read_b128 v[42:45], v131 offset:31296
	v_mfma_f32_16x16x32_bf16 v[18:21], v[18:21], v[70:73], v[134:137]
	s_waitcnt lgkmcnt(0)
	v_mfma_f32_16x16x32_bf16 v[134:137], v[42:45], v[70:73], v[34:37]
	s_nop 2
	ds_read_b128 v[34:37], v131 offset:33600
	s_waitcnt lgkmcnt(0)
	s_waitcnt lgkmcnt(0)
	v_mfma_f32_16x16x32_bf16 v[6:9], v[34:37], v[66:69], v[6:9]
	v_mfma_f32_16x16x32_bf16 v[2:5], v[34:37], v[70:73], v[2:5]
	v_add_f32_e32 v34, 0, v109
	v_add_f32_e32 v34, v110, v34
	v_add_f32_e32 v34, v111, v34
	v_add_f32_e32 v34, v112, v34
	v_add_f32_e32 v34, v113, v34
	v_add_f32_e32 v34, v114, v34
	v_add_f32_e32 v34, v88, v34
	v_add_f32_e32 v34, v89, v34
	v_add_f32_e32 v34, v90, v34
	v_add_f32_e32 v34, v91, v34
	v_add_f32_e32 v34, v92, v34
	v_add_f32_e32 v34, v93, v34
	v_add_f32_e32 v34, v115, v34
	v_add_f32_e32 v34, v116, v34
	v_add_f32_e32 v34, v117, v34
	v_add_f32_e32 v34, v118, v34
	v_mfma_f32_16x16x32_bf16 v[38:41], v[22:25], v[66:69], v[138:141]
	v_mfma_f32_16x16x32_bf16 v[82:85], v[54:57], v[66:69], v[46:49]
	v_mfma_f32_16x16x32_bf16 v[30:33], v[42:45], v[66:69], v[30:33]
	v_add_f32_e32 v66, v132, v34
	v_mov_b32_e32 v34, v1
	s_nop 1
	v_permlane16_swap_b32_e32 v1, v34
	v_add_f32_e32 v1, v1, v34
	v_mov_b32_e32 v34, v1
	s_nop 1
	v_permlane32_swap_b32_e32 v1, v34
	v_add_f32_e32 v1, v1, v34
	v_div_scale_f32 v34, s[18:19], v1, v1, 1.0
	v_rcp_f32_e32 v35, v34
	v_mfma_f32_16x16x32_bf16 v[22:25], v[22:25], v[70:73], v[142:145]
	v_mov_b32_e32 v69, v0
	v_mov_b32_e32 v70, v0
	v_fma_f32 v36, -v34, v35, 1.0
	v_fmac_f32_e32 v35, v36, v35
	v_div_scale_f32 v36, vcc, 1.0, v1, 1.0
	v_mul_f32_e32 v37, v36, v35
	v_fma_f32 v42, -v34, v37, v36
	v_fmac_f32_e32 v37, v42, v35
	v_fma_f32 v34, -v34, v37, v36
	v_div_fmas_f32 v34, v34, v35, v37
	v_div_fixup_f32 v34, v34, v1, 1.0
	v_mov_b32_e32 v1, v66
	s_nop 1
	v_permlane16_swap_b32_e32 v66, v1
	v_add_f32_e32 v1, v66, v1
	v_pk_mul_f32 v[64:65], v[16:17], v[34:35] op_sel_hi:[1,0]
	v_pk_mul_f32 v[62:63], v[14:15], v[34:35] op_sel_hi:[1,0]
	v_pk_mul_f32 v[60:61], v[28:29], v[34:35] op_sel_hi:[1,0]
	v_pk_mul_f32 v[58:59], v[26:27], v[34:35] op_sel_hi:[1,0]
	v_pk_mul_f32 v[56:57], v[40:41], v[34:35] op_sel_hi:[1,0]
	v_pk_mul_f32 v[54:55], v[38:39], v[34:35] op_sel_hi:[1,0]
	v_pk_mul_f32 v[52:53], v[52:53], v[34:35] op_sel_hi:[1,0]
	v_pk_mul_f32 v[50:51], v[50:51], v[34:35] op_sel_hi:[1,0]
	v_pk_mul_f32 v[48:49], v[122:123], v[34:35] op_sel_hi:[1,0]
	v_pk_mul_f32 v[46:47], v[120:121], v[34:35] op_sel_hi:[1,0]
	v_pk_mul_f32 v[44:45], v[84:85], v[34:35] op_sel_hi:[1,0]
	v_pk_mul_f32 v[42:43], v[82:83], v[34:35] op_sel_hi:[1,0]
	v_pk_mul_f32 v[40:41], v[32:33], v[34:35] op_sel_hi:[1,0]
	v_pk_mul_f32 v[38:39], v[30:31], v[34:35] op_sel_hi:[1,0]
	v_pk_mul_f32 v[36:37], v[8:9], v[34:35] op_sel_hi:[1,0]
	v_pk_mul_f32 v[34:35], v[6:7], v[34:35] op_sel_hi:[1,0]
	v_mov_b32_e32 v6, v1
	s_nop 1
	v_permlane32_swap_b32_e32 v1, v6
	v_add_f32_e32 v1, v1, v6
	v_div_scale_f32 v6, s[18:19], v1, v1, 1.0
	v_rcp_f32_e32 v7, v6
	s_nop 0
	v_fma_f32 v8, -v6, v7, 1.0
	v_fmac_f32_e32 v7, v8, v7
	v_div_scale_f32 v8, vcc, 1.0, v1, 1.0
	v_mul_f32_e32 v9, v8, v7
	v_fma_f32 v14, -v6, v9, v8
	v_fmac_f32_e32 v9, v14, v7
	v_fma_f32 v6, -v6, v9, v8
	v_div_fmas_f32 v6, v6, v7, v9
	v_div_fixup_f32 v66, v6, v1, 1.0
	v_pk_mul_f32 v[32:33], v[12:13], v[66:67] op_sel_hi:[1,0]
	v_pk_mul_f32 v[30:31], v[10:11], v[66:67] op_sel_hi:[1,0]
	v_pk_mul_f32 v[28:29], v[20:21], v[66:67] op_sel_hi:[1,0]
	v_pk_mul_f32 v[26:27], v[18:19], v[66:67] op_sel_hi:[1,0]
	v_pk_mul_f32 v[24:25], v[24:25], v[66:67] op_sel_hi:[1,0]
	v_pk_mul_f32 v[22:23], v[22:23], v[66:67] op_sel_hi:[1,0]
	v_pk_mul_f32 v[20:21], v[76:77], v[66:67] op_sel_hi:[1,0]
	v_pk_mul_f32 v[18:19], v[74:75], v[66:67] op_sel_hi:[1,0]
	v_pk_mul_f32 v[16:17], v[80:81], v[66:67] op_sel_hi:[1,0]
	v_pk_mul_f32 v[14:15], v[78:79], v[66:67] op_sel_hi:[1,0]
	v_pk_mul_f32 v[12:13], v[126:127], v[66:67] op_sel_hi:[1,0]
	v_pk_mul_f32 v[10:11], v[124:125], v[66:67] op_sel_hi:[1,0]
	v_pk_mul_f32 v[8:9], v[136:137], v[66:67] op_sel_hi:[1,0]
	v_pk_mul_f32 v[6:7], v[134:135], v[66:67] op_sel_hi:[1,0]
	v_pk_mul_f32 v[4:5], v[4:5], v[66:67] op_sel_hi:[1,0]
	v_pk_mul_f32 v[2:3], v[2:3], v[66:67] op_sel_hi:[1,0]
	s_waitcnt vmcnt(0)
	v_mul_f32_e32 v68, v160, v161
	s_nop 1
	v_mov_b32_dpp v69, v68 quad_perm:[1,0,3,2] row_mask:0xf bank_mask:0xf
	v_fmac_f32_e32 v69, v160, v161
	s_nop 1
	v_add_f32_dpp v1, v69, v69 quad_perm:[2,3,0,1] row_mask:0xf bank_mask:0xf bound_ctrl:1
	s_waitcnt vmcnt(0)
	v_mul_f32_e32 v69, v162, v163
	s_nop 1
	v_mov_b32_dpp v70, v69 quad_perm:[1,0,3,2] row_mask:0xf bank_mask:0xf
	v_fmac_f32_e32 v70, v162, v163
	v_add_f32_dpp v1, v1, v1 row_half_mirror row_mask:0xf bank_mask:0xf bound_ctrl:1
	s_nop 0
	v_add_f32_dpp v67, v70, v70 quad_perm:[2,3,0,1] row_mask:0xf bank_mask:0xf bound_ctrl:1
	v_add_f32_dpp v1, v1, v1 row_mirror row_mask:0xf bank_mask:0xf bound_ctrl:1
	v_mov_b32_e32 v66, v1
	v_add_f32_dpp v67, v67, v67 row_half_mirror row_mask:0xf bank_mask:0xf bound_ctrl:1
	s_nop 0
	v_permlane16_swap_b32_e32 v1, v66
	v_add_f32_dpp v67, v67, v67 row_mirror row_mask:0xf bank_mask:0xf bound_ctrl:1
	v_mov_b32_e32 v68, v67
	s_nop 1
	v_permlane16_swap_b32_e32 v67, v68
	v_add_f32_e32 v1, v1, v66
	v_add_f32_e32 v67, v67, v68
	v_mov_b32_e32 v66, v1
	v_mov_b32_e32 v68, v67
	s_nop 0
	v_permlane32_swap_b32_e32 v1, v66
	v_permlane32_swap_b32_e32 v67, v68
	s_cbranch_scc0 .LBB0_1109
	v_or_b32_e32 v69, s58, v149
	s_add_i32 s4, 0, 0x12000
	v_mul_u32_u24_e32 v69, 0x210, v69
	v_add3_u32 v69, s4, v130, v69
	ds_write_b128 v69, v[62:65]
	ds_write_b128 v69, v[58:61] offset:64
	ds_write_b128 v69, v[54:57] offset:128
	ds_write_b128 v69, v[50:53] offset:192
	ds_write_b128 v69, v[46:49] offset:256
	ds_write_b128 v69, v[42:45] offset:320
	ds_write_b128 v69, v[38:41] offset:384
	ds_write_b128 v69, v[34:37] offset:448
	ds_write_b128 v69, v[30:33] offset:8448
	ds_write_b128 v69, v[26:29] offset:8512
	ds_write_b128 v69, v[22:25] offset:8576
	ds_write_b128 v69, v[18:21] offset:8640
	ds_write_b128 v69, v[14:17] offset:8704
	ds_write_b128 v69, v[10:13] offset:8768
	ds_write_b128 v69, v[6:9] offset:8832
	ds_write_b128 v69, v[2:5] offset:8896

.LBB0_1120:
	s_add_u32 s40, s16, s8
	s_addc_u32 s41, s17, s9
	v_lshlrev_b32_e32 v164, 2, v148
	global_load_dword v160, v164, s[40:41]
	global_load_dword v161, v164, s[40:41] offset:256
	global_load_dword v162, v164, s[40:41] offset:512
	global_load_dword v163, v164, s[40:41] offset:768
	v_sub_f32_e32 v66, v103, v137
	v_sub_f32_e32 v1, v102, v137
	v_exp_f32_e32 v102, v66
	v_sub_f32_e32 v66, v104, v137
	v_sub_f32_e32 v68, v68, v137
	v_exp_f32_e32 v103, v66
	v_sub_f32_e32 v66, v105, v137
	v_exp_f32_e32 v105, v68
	v_sub_f32_e32 v68, v69, v137
	v_exp_f32_e32 v106, v68
	v_sub_f32_e32 v68, v70, v137
	v_sub_f32_e32 v70, v82, v136
	v_exp_f32_e32 v109, v70
	v_sub_f32_e32 v70, v83, v136
	v_exp_f32_e32 v110, v70
	v_sub_f32_e32 v70, v84, v136
	v_exp_f32_e32 v111, v70
	v_sub_f32_e32 v70, v85, v136
	v_exp_f32_e32 v104, v66
	v_sub_f32_e32 v66, v98, v137
	v_exp_f32_e32 v112, v70
	v_sub_f32_e32 v70, v86, v136
	ds_read_b128 v[80:83], v133 offset:17408
	v_exp_f32_e32 v98, v66
	v_sub_f32_e32 v66, v99, v137
	v_exp_f32_e32 v113, v70
	v_sub_f32_e32 v70, v87, v136
	v_exp_f32_e32 v99, v66
	v_sub_f32_e32 v66, v100, v137
	v_exp_f32_e32 v114, v70
	v_sub_f32_e32 v70, v88, v136
	v_exp_f32_e32 v100, v66
	v_sub_f32_e32 v66, v101, v137
	v_exp_f32_e32 v88, v70
	v_sub_f32_e32 v70, v89, v136
	v_exp_f32_e32 v1, v1
	v_exp_f32_e32 v101, v66
	v_exp_f32_e32 v89, v70
	v_cvt_pk_bf16_f32 v77, v103, v104
	v_cvt_pk_bf16_f32 v76, v1, v102
	v_cvt_pk_bf16_f32 v78, v98, v99
	v_cvt_pk_bf16_f32 v79, v100, v101
	v_cvt_pk_bf16_f32 v120, v109, v110
	v_cvt_pk_bf16_f32 v121, v111, v112
	v_cvt_pk_bf16_f32 v122, v113, v114
	v_cvt_pk_bf16_f32 v123, v88, v89
	s_waitcnt lgkmcnt(0)
	v_mfma_f32_16x16x32_bf16 v[26:29], v[80:83], v[76:79], v[26:29]
	v_sub_f32_e32 v66, v94, v137
	v_sub_f32_e32 v70, v90, v136
	v_sub_f32_e32 v72, v72, v136
	v_mfma_f32_16x16x32_bf16 v[18:21], v[80:83], v[120:123], v[18:21]
	ds_read_b128 v[80:83], v133 offset:19712
	v_exp_f32_e32 v94, v66
	v_sub_f32_e32 v66, v95, v137
	s_waitcnt lgkmcnt(0)
	v_mfma_f32_16x16x32_bf16 v[128:131], v[80:83], v[120:123], v[2:5]
	s_nop 2
	ds_read_b128 v[2:5], v133 offset:22016
	v_exp_f32_e32 v90, v70
	v_sub_f32_e32 v70, v91, v136
	v_exp_f32_e32 v115, v72
	v_sub_f32_e32 v72, v73, v136
	v_exp_f32_e32 v95, v66
	v_sub_f32_e32 v66, v96, v137
	v_exp_f32_e32 v91, v70
	v_sub_f32_e32 v70, v92, v136
	v_exp_f32_e32 v116, v72
	v_sub_f32_e32 v72, v74, v136
	v_exp_f32_e32 v96, v66
	v_sub_f32_e32 v66, v97, v137
	v_exp_f32_e32 v107, v68
	v_sub_f32_e32 v68, v71, v137
	v_exp_f32_e32 v92, v70
	v_sub_f32_e32 v70, v93, v136
	v_exp_f32_e32 v117, v72
	v_sub_f32_e32 v72, v75, v136
	s_waitcnt lgkmcnt(0)
	v_mfma_f32_16x16x32_bf16 v[136:139], v[2:5], v[76:79], v[14:17]
	v_exp_f32_e32 v97, v66
	v_exp_f32_e32 v108, v68
	v_exp_f32_e32 v93, v70
	v_mfma_f32_16x16x32_bf16 v[140:143], v[2:5], v[120:123], v[10:13]
	ds_read_b128 v[2:5], v133 offset:24320
	v_exp_f32_e32 v118, v72
	v_cvt_pk_bf16_f32 v66, v94, v95
	s_waitcnt lgkmcnt(0)
	v_mfma_f32_16x16x32_bf16 v[150:153], v[2:5], v[76:79], v[30:33]
	ds_read_b128 v[10:13], v133 offset:17472
	v_cvt_pk_bf16_f32 v67, v96, v97
	v_cvt_pk_bf16_f32 v68, v105, v106
	v_mfma_f32_16x16x32_bf16 v[154:157], v[2:5], v[120:123], v[22:25]
	ds_read_b128 v[2:5], v133 offset:26624
	v_cvt_pk_bf16_f32 v69, v107, v108
	v_cvt_pk_bf16_f32 v70, v90, v91
	v_mfma_f32_16x16x32_bf16 v[124:127], v[80:83], v[76:79], v[6:9]
	v_cvt_pk_bf16_f32 v71, v92, v93
	v_cvt_pk_bf16_f32 v72, v115, v116
	v_cvt_pk_bf16_f32 v73, v117, v118
	s_waitcnt lgkmcnt(0)
	v_mfma_f32_16x16x32_bf16 v[80:83], v[2:5], v[76:79], v[38:41]
	ds_read_b128 v[22:25], v133 offset:22080
	v_add_f32_e32 v1, 0, v1
	v_add_f32_e32 v1, v102, v1
	v_mfma_f32_16x16x32_bf16 v[84:87], v[2:5], v[120:123], v[34:37]
	ds_read_b128 v[2:5], v133 offset:28928
	v_add_f32_e32 v1, v103, v1
	v_add_f32_e32 v1, v104, v1
	s_waitcnt lgkmcnt(0)
	v_mfma_f32_16x16x32_bf16 v[46:49], v[2:5], v[76:79], v[46:49]
	v_add_f32_e32 v1, v98, v1
	v_add_f32_e32 v1, v99, v1
	v_add_f32_e32 v1, v100, v1
	v_mfma_f32_16x16x32_bf16 v[42:45], v[2:5], v[120:123], v[42:45]
	ds_read_b128 v[2:5], v133 offset:31232
	v_add_f32_e32 v1, v101, v1
	v_add_f32_e32 v1, v94, v1
	s_waitcnt lgkmcnt(0)
	v_mfma_f32_16x16x32_bf16 v[30:33], v[2:5], v[76:79], v[54:57]
	s_nop 2
	ds_read_b128 v[54:57], v133 offset:24384
	v_add_f32_e32 v1, v95, v1
	v_add_f32_e32 v1, v96, v1
	v_mfma_f32_16x16x32_bf16 v[34:37], v[2:5], v[120:123], v[50:53]
	ds_read_b128 v[2:5], v133 offset:33536
	v_add_f32_e32 v1, v97, v1
	v_add_f32_e32 v1, v105, v1
	v_mfma_f32_16x16x32_bf16 v[14:17], v[10:13], v[66:69], v[26:29]
	v_add_f32_e32 v1, v106, v1
	v_add_f32_e32 v1, v107, v1
	v_add_f32_e32 v1, v108, v1
	v_mfma_f32_16x16x32_bf16 v[10:13], v[10:13], v[70:73], v[18:21]
	v_add_f32_e32 v1, v135, v1
	s_add_u32 s4, s16, s8
	s_addc_u32 s5, s17, s9
	ds_read_b128 v[18:21], v133 offset:19776
	s_waitcnt lgkmcnt(1)
	v_mfma_f32_16x16x32_bf16 v[6:9], v[2:5], v[76:79], v[62:65]
	s_cmp_eq_u32 s39, 1
	v_mfma_f32_16x16x32_bf16 v[50:53], v[54:57], v[66:69], v[150:153]
	v_mfma_f32_16x16x32_bf16 v[74:77], v[54:57], v[70:73], v[154:157]
	ds_read_b128 v[54:57], v133 offset:26688
	v_mfma_f32_16x16x32_bf16 v[2:5], v[2:5], v[120:123], v[58:61]
	s_waitcnt lgkmcnt(0)
	v_mfma_f32_16x16x32_bf16 v[120:123], v[54:57], v[66:69], v[80:83]
	v_mfma_f32_16x16x32_bf16 v[78:81], v[54:57], v[70:73], v[84:87]
	ds_read_b128 v[54:57], v133 offset:28992
	v_mfma_f32_16x16x32_bf16 v[26:29], v[18:21], v[66:69], v[124:127]
	s_waitcnt lgkmcnt(0)
	v_mfma_f32_16x16x32_bf16 v[124:127], v[54:57], v[70:73], v[42:45]
	s_nop 2
	ds_read_b128 v[42:45], v133 offset:31296
	v_mfma_f32_16x16x32_bf16 v[18:21], v[18:21], v[70:73], v[128:131]
	s_waitcnt lgkmcnt(0)
	v_mfma_f32_16x16x32_bf16 v[128:131], v[42:45], v[70:73], v[34:37]
	s_nop 2
	ds_read_b128 v[34:37], v133 offset:33600
	s_waitcnt lgkmcnt(0)
	s_waitcnt lgkmcnt(0)
	v_mfma_f32_16x16x32_bf16 v[6:9], v[34:37], v[66:69], v[6:9]
	v_mfma_f32_16x16x32_bf16 v[2:5], v[34:37], v[70:73], v[2:5]
	v_add_f32_e32 v34, 0, v109
	v_add_f32_e32 v34, v110, v34
	v_add_f32_e32 v34, v111, v34
	v_add_f32_e32 v34, v112, v34
	v_add_f32_e32 v34, v113, v34
	v_add_f32_e32 v34, v114, v34
	v_add_f32_e32 v34, v88, v34
	v_add_f32_e32 v34, v89, v34
	v_add_f32_e32 v34, v90, v34
	v_add_f32_e32 v34, v91, v34
	v_add_f32_e32 v34, v92, v34
	v_add_f32_e32 v34, v93, v34
	v_add_f32_e32 v34, v115, v34
	v_add_f32_e32 v34, v116, v34
	v_add_f32_e32 v34, v117, v34
	v_add_f32_e32 v34, v118, v34
	v_mfma_f32_16x16x32_bf16 v[38:41], v[22:25], v[66:69], v[136:139]
	v_mfma_f32_16x16x32_bf16 v[82:85], v[54:57], v[66:69], v[46:49]
	v_mfma_f32_16x16x32_bf16 v[30:33], v[42:45], v[66:69], v[30:33]
	v_add_f32_e32 v66, v134, v34
	v_mov_b32_e32 v34, v1
	s_nop 1
	v_permlane16_swap_b32_e32 v1, v34
	v_add_f32_e32 v1, v1, v34
	v_mov_b32_e32 v34, v1
	s_nop 1
	v_permlane32_swap_b32_e32 v1, v34
	v_add_f32_e32 v1, v1, v34
	v_div_scale_f32 v34, s[16:17], v1, v1, 1.0
	v_rcp_f32_e32 v35, v34
	v_mfma_f32_16x16x32_bf16 v[22:25], v[22:25], v[70:73], v[140:143]
	v_mov_b32_e32 v69, v0
	v_mov_b32_e32 v70, v0
	v_fma_f32 v36, -v34, v35, 1.0
	v_fmac_f32_e32 v35, v36, v35
	v_div_scale_f32 v36, vcc, 1.0, v1, 1.0
	v_mul_f32_e32 v37, v36, v35
	v_fma_f32 v42, -v34, v37, v36
	v_fmac_f32_e32 v37, v42, v35
	v_fma_f32 v34, -v34, v37, v36
	v_div_fmas_f32 v34, v34, v35, v37
	v_div_fixup_f32 v34, v34, v1, 1.0
	v_mov_b32_e32 v1, v66
	s_nop 1
	v_permlane16_swap_b32_e32 v66, v1
	v_add_f32_e32 v1, v66, v1
	v_pk_mul_f32 v[64:65], v[16:17], v[34:35] op_sel_hi:[1,0]
	v_pk_mul_f32 v[62:63], v[14:15], v[34:35] op_sel_hi:[1,0]
	v_pk_mul_f32 v[60:61], v[28:29], v[34:35] op_sel_hi:[1,0]
	v_pk_mul_f32 v[58:59], v[26:27], v[34:35] op_sel_hi:[1,0]
	v_pk_mul_f32 v[56:57], v[40:41], v[34:35] op_sel_hi:[1,0]
	v_pk_mul_f32 v[54:55], v[38:39], v[34:35] op_sel_hi:[1,0]
	v_pk_mul_f32 v[52:53], v[52:53], v[34:35] op_sel_hi:[1,0]
	v_pk_mul_f32 v[50:51], v[50:51], v[34:35] op_sel_hi:[1,0]
	v_pk_mul_f32 v[48:49], v[122:123], v[34:35] op_sel_hi:[1,0]
	v_pk_mul_f32 v[46:47], v[120:121], v[34:35] op_sel_hi:[1,0]
	v_pk_mul_f32 v[44:45], v[84:85], v[34:35] op_sel_hi:[1,0]
	v_pk_mul_f32 v[42:43], v[82:83], v[34:35] op_sel_hi:[1,0]
	v_pk_mul_f32 v[40:41], v[32:33], v[34:35] op_sel_hi:[1,0]
	v_pk_mul_f32 v[38:39], v[30:31], v[34:35] op_sel_hi:[1,0]
	v_pk_mul_f32 v[36:37], v[8:9], v[34:35] op_sel_hi:[1,0]
	v_pk_mul_f32 v[34:35], v[6:7], v[34:35] op_sel_hi:[1,0]
	v_mov_b32_e32 v6, v1
	s_nop 1
	v_permlane32_swap_b32_e32 v1, v6
	v_add_f32_e32 v1, v1, v6
	v_div_scale_f32 v6, s[16:17], v1, v1, 1.0
	v_rcp_f32_e32 v7, v6
	s_nop 0
	v_fma_f32 v8, -v6, v7, 1.0
	v_fmac_f32_e32 v7, v8, v7
	v_div_scale_f32 v8, vcc, 1.0, v1, 1.0
	v_mul_f32_e32 v9, v8, v7
	v_fma_f32 v14, -v6, v9, v8
	v_fmac_f32_e32 v9, v14, v7
	v_fma_f32 v6, -v6, v9, v8
	v_div_fmas_f32 v6, v6, v7, v9
	v_div_fixup_f32 v66, v6, v1, 1.0
	v_pk_mul_f32 v[32:33], v[12:13], v[66:67] op_sel_hi:[1,0]
	v_pk_mul_f32 v[30:31], v[10:11], v[66:67] op_sel_hi:[1,0]
	v_pk_mul_f32 v[28:29], v[20:21], v[66:67] op_sel_hi:[1,0]
	v_pk_mul_f32 v[26:27], v[18:19], v[66:67] op_sel_hi:[1,0]
	v_pk_mul_f32 v[24:25], v[24:25], v[66:67] op_sel_hi:[1,0]
	v_pk_mul_f32 v[22:23], v[22:23], v[66:67] op_sel_hi:[1,0]
	v_pk_mul_f32 v[20:21], v[76:77], v[66:67] op_sel_hi:[1,0]
	v_pk_mul_f32 v[18:19], v[74:75], v[66:67] op_sel_hi:[1,0]
	v_pk_mul_f32 v[16:17], v[80:81], v[66:67] op_sel_hi:[1,0]
	v_pk_mul_f32 v[14:15], v[78:79], v[66:67] op_sel_hi:[1,0]
	v_pk_mul_f32 v[12:13], v[126:127], v[66:67] op_sel_hi:[1,0]
	v_pk_mul_f32 v[10:11], v[124:125], v[66:67] op_sel_hi:[1,0]
	v_pk_mul_f32 v[8:9], v[130:131], v[66:67] op_sel_hi:[1,0]
	v_pk_mul_f32 v[6:7], v[128:129], v[66:67] op_sel_hi:[1,0]
	v_pk_mul_f32 v[4:5], v[4:5], v[66:67] op_sel_hi:[1,0]
	v_pk_mul_f32 v[2:3], v[2:3], v[66:67] op_sel_hi:[1,0]
	s_waitcnt vmcnt(0)
	v_mul_f32_e32 v68, v160, v161
	s_nop 1
	v_mov_b32_dpp v69, v68 quad_perm:[1,0,3,2] row_mask:0xf bank_mask:0xf
	v_fmac_f32_e32 v69, v160, v161
	s_nop 1
	v_add_f32_dpp v1, v69, v69 quad_perm:[2,3,0,1] row_mask:0xf bank_mask:0xf bound_ctrl:1
	s_waitcnt vmcnt(0)
	v_mul_f32_e32 v69, v162, v163
	s_nop 1
	v_mov_b32_dpp v70, v69 quad_perm:[1,0,3,2] row_mask:0xf bank_mask:0xf
	v_fmac_f32_e32 v70, v162, v163
	v_add_f32_dpp v1, v1, v1 row_half_mirror row_mask:0xf bank_mask:0xf bound_ctrl:1
	s_nop 0
	v_add_f32_dpp v67, v70, v70 quad_perm:[2,3,0,1] row_mask:0xf bank_mask:0xf bound_ctrl:1
	v_add_f32_dpp v1, v1, v1 row_mirror row_mask:0xf bank_mask:0xf bound_ctrl:1
	v_mov_b32_e32 v66, v1
	v_add_f32_dpp v67, v67, v67 row_half_mirror row_mask:0xf bank_mask:0xf bound_ctrl:1
	s_nop 0
	v_permlane16_swap_b32_e32 v1, v66
	v_add_f32_dpp v67, v67, v67 row_mirror row_mask:0xf bank_mask:0xf bound_ctrl:1
	v_mov_b32_e32 v68, v67
	s_nop 1
	v_permlane16_swap_b32_e32 v67, v68
	v_add_f32_e32 v1, v1, v66
	v_add_f32_e32 v67, v67, v68
	v_mov_b32_e32 v66, v1
	v_mov_b32_e32 v68, v67
	s_nop 0
	v_permlane32_swap_b32_e32 v1, v66
	v_permlane32_swap_b32_e32 v67, v68
	s_cbranch_scc0 .LBB0_1122
	v_or_b32_e32 v69, s38, v145
	s_add_i32 s4, 0, 0x12000
	v_mul_u32_u24_e32 v69, 0x210, v69
	v_add3_u32 v69, s4, v132, v69
	ds_write_b128 v69, v[62:65]
	ds_write_b128 v69, v[58:61] offset:64
	ds_write_b128 v69, v[54:57] offset:128
	ds_write_b128 v69, v[50:53] offset:192
	ds_write_b128 v69, v[46:49] offset:256
	ds_write_b128 v69, v[42:45] offset:320
	ds_write_b128 v69, v[38:41] offset:384
	ds_write_b128 v69, v[34:37] offset:448
	ds_write_b128 v69, v[30:33] offset:8448
	ds_write_b128 v69, v[26:29] offset:8512
	ds_write_b128 v69, v[22:25] offset:8576
	ds_write_b128 v69, v[18:21] offset:8640
	ds_write_b128 v69, v[14:17] offset:8704
	ds_write_b128 v69, v[10:13] offset:8768
	ds_write_b128 v69, v[6:9] offset:8832
	ds_write_b128 v69, v[2:5] offset:8896
